# local phase: workgroups >= 56 rotate over all four unit kinds ((k+w)&3)
# baseline (speedup 1.0000x reference)
.LBB0_270:
	s_or_b64 exec, exec, s[0:1]
	v_readlane_b32 s0, v255, 7
	v_readlane_b32 s1, v255, 8
	s_andn2_b64 vcc, exec, s[0:1]
	s_waitcnt lgkmcnt(0)
	s_barrier
	s_cbranch_vccnz .LBB0_521
	v_readlane_b32 s0, v255, 25
	s_lshl_b32 s48, s0, 9
	s_lshl_b32 s8, s0, 4
	s_lshl_b32 s9, s0, 12
	s_lshl_b32 s6, s0, 8
	s_mov_b32 s7, s49
	s_lshl_b32 s10, s0, 10
	s_mov_b32 s11, s49
	s_lshl_b32 s20, s0, 1
	s_lshl_b32 s14, s0, 11
	s_mov_b32 s15, s49
	s_lshl_b32 s21, s0, 3
	s_lshl_b64 s[16:17], s[48:49], 2
	v_readlane_b32 s22, v255, 0
	v_readlane_b32 s1, v255, 26
	s_cmpk_eq_i32 s36, 0x100
	s_cselect_b32 s101, 0, -1
	s_cmp_eq_u32 s101, -1
	s_cbranch_scc1 .Lrot_e
	s_cmp_lt_u32 s22, 56
	s_cbranch_scc1 .Lrot3_e
	s_and_b32 s100, s22, 3
	s_mul_i32 s100, s100, 0x108
	s_add_i32 s22, s22, s100
	s_branch .Lrot_e
.Lrot3_e:
	s_mul_i32 s100, s22, 171
	s_lshr_b32 s100, s100, 9
	s_mul_i32 s100, s100, 3
	s_sub_i32 s100, s22, s100
	s_mul_i32 s100, s100, 0x108
	s_add_i32 s22, s22, s100

.LBB0_273:
	s_cmp_eq_u32 s101, -1
	s_cbranch_scc1 .Llc_stride
	s_add_i32 s101, s101, 1
	v_readlane_b32 s100, v255, 0
	s_nop 3
	s_cmp_lt_u32 s100, 56
	s_cbranch_scc1 .Lrot3_l
	s_cmp_gt_u32 s101, 3
	s_cbranch_scc1 .LBB0_521
	s_add_i32 s22, s101, s100
	s_and_b32 s22, s22, 3
	s_mul_i32 s22, s22, 0x108
	s_add_i32 s22, s22, s100
	s_branch .LBB0_274
.Lrot3_l:
	s_cmp_lt_u32 s101, 3
	s_cbranch_scc0 .Llc_k3
	s_mul_i32 s22, s100, 171
	s_lshr_b32 s22, s22, 9
	s_mul_i32 s22, s22, 3
	s_sub_i32 s22, s100, s22
	s_add_i32 s22, s22, s101
	s_cmp_gt_u32 s22, 2
	s_cselect_b32 s0, 3, 0
	s_sub_i32 s22, s22, s0
	s_mul_i32 s22, s22, 0x108
	s_add_i32 s22, s22, s100
	s_branch .LBB0_274
